# attention unit rewritten by hand: both value halves per unit (QK^T and softmax once), LDS-DMA K/V staging, one barrier per tile
# speedup vs baseline: 1.0341x; 1.0300x over previous
.LBB0_528:
	s_or_b64 exec, exec, s[6:7]
	v_mov_b32_e32 v0, s31
	s_waitcnt vmcnt(0) lgkmcnt(0)
	s_barrier
	ds_read_b32 v0, v0
	s_movk_i32 s1, 0x81f
	s_mov_b64 s[6:7], -1
	s_waitcnt lgkmcnt(0)
	s_barrier
	v_cmp_lt_i32_e32 vcc, s1, v0
	v_readfirstlane_b32 s0, v0
	s_cbranch_vccnz .LBB0_523
	s_cmp_lt_i32 s0, 32
	s_cselect_b64 s[56:57], -1, 0
	s_add_i32 s1, s0, 0xfffffde0
	s_cmpk_lt_u32 s1, 0x200
	s_cselect_b64 s[6:7], -1, 0
	s_or_b64 s[6:7], s[56:57], s[6:7]
	s_andn2_b64 vcc, exec, s[6:7]
	s_mov_b64 s[6:7], -1
	s_cbranch_vccz .LBB0_555
	s_sub_i32 s46, s0, 32
	s_cmpk_lt_u32 s0, 0x220
	s_cselect_b32 s46, s46, s1
	s_bitcmp1_b32 s46, 0
	s_cbranch_scc1 .Lam_skip
	s_cmpk_gt_u32 s46, 0x1ff
	s_cbranch_scc1 .Lam_ctx
	s_lshr_b32 s8, s46, 8
	s_bfe_u32 s9, s46, 0x30002
	s_lshl_b32 s10, s8, 11
	s_lshl_b32 s9, s9, 8
	s_add_i32 s10, s10, s9
	s_add_i32 s10, s10, 0x2000
	s_mulk_i32 s8, 0x900
	s_add_i32 s11, s8, 0x2000
	s_bfe_u32 s12, s46, 0x30005
	s_mov_b32 s13, 36
	s_branch .Lam_go
.Lam_ctx:
	s_sub_i32 s8, s46, 0x200
	s_lshr_b32 s10, s8, 5
	s_lshl_b32 s10, s10, 8
	s_mov_b32 s11, s10
	s_bfe_u32 s12, s8, 0x30002
	s_mov_b32 s13, 4
.Lam_go:
	s_bfe_u32 s14, s46, 0x10001
	s_lshl_b32 s15, s12, 9
	s_lshl_b32 s28, s14, 8
	s_add_i32 s28, s28, s15
	s_lshl_b32 s8, s10, 12
	s_add_i32 s8, s8, s28
	s_add_u32 s16, s40, s8
	s_addc_u32 s17, s41, 0
	s_lshl_b32 s8, s11, 12
	s_add_i32 s9, s8, s28
	s_add_u32 s18, s42, s9
	s_addc_u32 s19, s43, 0
	s_add_i32 s9, s8, s15
	s_add_u32 s20, s44, s9
	s_addc_u32 s21, s45, 0
	s_lshl_b32 s8, s10, 13
	s_lshl_b32 s9, s28, 1
	s_add_i32 s8, s8, s9
	s_add_u32 s22, s48, s8
	s_addc_u32 s23, s49, 0
	v_mbcnt_lo_u32_b32 v96, -1, 0
	v_mbcnt_hi_u32_b32 v96, -1, v96
	s_lshr_b32 s36, s84, 6
	s_lshl_b32 s38, s36, 3
	s_lshl_b32 s39, s36, 11
	s_lshl_b32 s47, s36, 12
	s_add_i32 s47, s47, 0x4000
	s_lshl_b32 s50, s36, 8
	s_add_i32 s50, s50, 0x18000
	v_and_b32_e32 v240, 31, v96
	v_lshrrev_b32_e32 v241, 5, v96
	s_lshl_b32 s37, s36, 5
	v_add_u32_e32 v242, s37, v240
	v_lshlrev_b32_e32 v242, 12, v242
	v_lshl_add_u32 v242, v241, 4, v242
	global_load_dwordx4 v[130:133], v242, s[16:17]
	global_load_dwordx4 v[134:137], v242, s[16:17] offset:32
	global_load_dwordx4 v[138:141], v242, s[16:17] offset:64
	global_load_dwordx4 v[142:145], v242, s[16:17] offset:96
	global_load_dwordx4 v[146:149], v242, s[16:17] offset:128
	global_load_dwordx4 v[150:153], v242, s[16:17] offset:160
	global_load_dwordx4 v[154:157], v242, s[16:17] offset:192
	global_load_dwordx4 v[158:161], v242, s[16:17] offset:224
	v_lshlrev_b32_e32 v243, 8, v240
	v_and_b32_e32 v238, 7, v240
	v_lshlrev_b32_e32 v238, 4, v238
	v_lshlrev_b32_e32 v239, 4, v241
	v_mov_b32_e32 v228, v239
	v_xor_b32_e32 v228, v228, v238
	v_add_u32_e32 v228, v228, v243
	v_or_b32_e32 v229, 32, v239
	v_xor_b32_e32 v229, v229, v238
	v_add_u32_e32 v229, v229, v243
	v_or_b32_e32 v230, 64, v239
	v_xor_b32_e32 v230, v230, v238
	v_add_u32_e32 v230, v230, v243
	v_or_b32_e32 v231, 96, v239
	v_xor_b32_e32 v231, v231, v238
	v_add_u32_e32 v231, v231, v243
	v_or_b32_e32 v232, 128, v239
	v_xor_b32_e32 v232, v232, v238
	v_add_u32_e32 v232, v232, v243
	v_or_b32_e32 v233, 160, v239
	v_xor_b32_e32 v233, v233, v238
	v_add_u32_e32 v233, v233, v243
	v_or_b32_e32 v234, 192, v239
	v_xor_b32_e32 v234, v234, v238
	v_add_u32_e32 v234, v234, v243
	v_or_b32_e32 v235, 224, v239
	v_xor_b32_e32 v235, v235, v238
	v_add_u32_e32 v235, v235, v243
	v_and_b32_e32 v238, 3, v96
	v_lshlrev_b32_e32 v236, 3, v238
	v_bfe_u32 v238, v96, 2, 2
	v_lshl_or_b32 v236, v238, 6, v236
	v_bfe_u32 v238, v96, 4, 1
	v_lshl_or_b32 v236, v238, 5, v236
	v_lshl_or_b32 v236, v241, 8, v236
	v_add_u32_e32 v237, 0x10000, v236
	v_add_u32_e32 v236, 0x4000, v236
	v_lshrrev_b32_e32 v238, 4, v96
	v_and_b32_e32 v239, 15, v96
	v_add_u32_e32 v243, 0, v238
	v_xor_b32_e32 v244, v239, v243
	v_lshlrev_b32_e32 v244, 4, v244
	v_add_u32_e32 v243, s38, v243
	v_lshl_add_u32 v244, v243, 12, v244
	v_add_u32_e32 v243, 4, v238
	v_xor_b32_e32 v245, v239, v243
	v_lshlrev_b32_e32 v245, 4, v245
	v_add_u32_e32 v243, s38, v243
	v_lshl_add_u32 v245, v243, 12, v245
	v_lshrrev_b32_e32 v238, 2, v240
	v_add_u32_e32 v238, s38, v238
	v_and_b32_e32 v239, 0xfffffff3, v238
	v_and_b32_e32 v243, 4, v238
	v_lshl_or_b32 v239, v243, 1, v239
	v_and_b32_e32 v243, 8, v238
	v_lshrrev_b32_e32 v243, 1, v243
	v_or_b32_e32 v239, v239, v243
	v_lshlrev_b32_e32 v239, 12, v239
	v_and_b32_e32 v238, 3, v240
	v_lshlrev_b32_e32 v238, 4, v238
	v_add_u32_e32 v243, 0, v241
	v_lshl_add_u32 v243, v243, 6, v238
	v_add_u32_e32 v246, v239, v243
	v_add_u32_e32 v243, 2, v241
	v_lshl_add_u32 v243, v243, 6, v238
	v_add_u32_e32 v247, v239, v243
	v_add_u32_e32 v243, 4, v241
	v_lshl_add_u32 v243, v243, 6, v238
	v_add_u32_e32 v248, v239, v243
	v_add_u32_e32 v243, 6, v241
	v_lshl_add_u32 v243, v243, 6, v238
	v_add_u32_e32 v249, v239, v243
	v_mov_b32_e32 v238, 0xf149f2ca
	v_mov_b32_e32 v239, 0
	v_mov_b32_e32 v0, 0
	v_mov_b32_e32 v1, 0
	v_mov_b32_e32 v2, 0
	v_mov_b32_e32 v3, 0
	v_mov_b32_e32 v4, 0
	v_mov_b32_e32 v5, 0
	v_mov_b32_e32 v6, 0
	v_mov_b32_e32 v7, 0
	v_mov_b32_e32 v8, 0
	v_mov_b32_e32 v9, 0
	v_mov_b32_e32 v10, 0
	v_mov_b32_e32 v11, 0
	v_mov_b32_e32 v12, 0
	v_mov_b32_e32 v13, 0
	v_mov_b32_e32 v14, 0
	v_mov_b32_e32 v15, 0
	v_mov_b32_e32 v16, 0
	v_mov_b32_e32 v17, 0
	v_mov_b32_e32 v18, 0
	v_mov_b32_e32 v19, 0
	v_mov_b32_e32 v20, 0
	v_mov_b32_e32 v21, 0
	v_mov_b32_e32 v22, 0
	v_mov_b32_e32 v23, 0
	v_mov_b32_e32 v24, 0
	v_mov_b32_e32 v25, 0
	v_mov_b32_e32 v26, 0
	v_mov_b32_e32 v27, 0
	v_mov_b32_e32 v28, 0
	v_mov_b32_e32 v29, 0
	v_mov_b32_e32 v30, 0
	v_mov_b32_e32 v31, 0
	v_mov_b32_e32 v32, 0
	v_mov_b32_e32 v33, 0
	v_mov_b32_e32 v34, 0
	v_mov_b32_e32 v35, 0
	v_mov_b32_e32 v36, 0
	v_mov_b32_e32 v37, 0
	v_mov_b32_e32 v38, 0
	v_mov_b32_e32 v39, 0
	v_mov_b32_e32 v40, 0
	v_mov_b32_e32 v41, 0
	v_mov_b32_e32 v42, 0
	v_mov_b32_e32 v43, 0
	v_mov_b32_e32 v44, 0
	v_mov_b32_e32 v45, 0
	v_mov_b32_e32 v46, 0
	v_mov_b32_e32 v47, 0
	v_mov_b32_e32 v48, 0
	v_mov_b32_e32 v49, 0
	v_mov_b32_e32 v50, 0
	v_mov_b32_e32 v51, 0
	v_mov_b32_e32 v52, 0
	v_mov_b32_e32 v53, 0
	v_mov_b32_e32 v54, 0
	v_mov_b32_e32 v55, 0
	v_mov_b32_e32 v56, 0
	v_mov_b32_e32 v57, 0
	v_mov_b32_e32 v58, 0
	v_mov_b32_e32 v59, 0
	v_mov_b32_e32 v60, 0
	v_mov_b32_e32 v61, 0
	v_mov_b32_e32 v62, 0
	v_mov_b32_e32 v63, 0
	v_mov_b32_e32 v64, 0
	v_mov_b32_e32 v65, 0
	v_mov_b32_e32 v66, 0
	v_mov_b32_e32 v67, 0
	v_mov_b32_e32 v68, 0
	v_mov_b32_e32 v69, 0
	v_mov_b32_e32 v70, 0
	v_mov_b32_e32 v71, 0
	v_mov_b32_e32 v72, 0
	v_mov_b32_e32 v73, 0
	v_mov_b32_e32 v74, 0
	v_mov_b32_e32 v75, 0
	v_mov_b32_e32 v76, 0
	v_mov_b32_e32 v77, 0
	v_mov_b32_e32 v78, 0
	v_mov_b32_e32 v79, 0
	v_mov_b32_e32 v80, 0
	v_mov_b32_e32 v81, 0
	v_mov_b32_e32 v82, 0
	v_mov_b32_e32 v83, 0
	v_mov_b32_e32 v84, 0
	v_mov_b32_e32 v85, 0
	v_mov_b32_e32 v86, 0
	v_mov_b32_e32 v87, 0
	v_mov_b32_e32 v88, 0
	v_mov_b32_e32 v89, 0
	v_mov_b32_e32 v90, 0
	v_mov_b32_e32 v91, 0
	v_mov_b32_e32 v92, 0
	v_mov_b32_e32 v93, 0
	v_mov_b32_e32 v94, 0
	v_mov_b32_e32 v95, 0
	v_mov_b32_e32 v98, 0
	v_mov_b32_e32 v99, 0
	v_mov_b32_e32 v100, 0
	v_mov_b32_e32 v101, 0
	v_mov_b32_e32 v102, 0
	v_mov_b32_e32 v103, 0
	v_mov_b32_e32 v104, 0
	v_mov_b32_e32 v105, 0
	v_mov_b32_e32 v106, 0
	v_mov_b32_e32 v107, 0
	v_mov_b32_e32 v108, 0
	v_mov_b32_e32 v109, 0
	v_mov_b32_e32 v110, 0
	v_mov_b32_e32 v111, 0
	v_mov_b32_e32 v112, 0
	v_mov_b32_e32 v113, 0
	v_mov_b32_e32 v114, 0
	v_mov_b32_e32 v115, 0
	v_mov_b32_e32 v116, 0
	v_mov_b32_e32 v117, 0
	v_mov_b32_e32 v118, 0
	v_mov_b32_e32 v119, 0
	v_mov_b32_e32 v120, 0
	v_mov_b32_e32 v121, 0
	v_mov_b32_e32 v122, 0
	v_mov_b32_e32 v123, 0
	v_mov_b32_e32 v124, 0
	v_mov_b32_e32 v125, 0
	v_mov_b32_e32 v126, 0
	v_mov_b32_e32 v127, 0
	v_mov_b32_e32 v128, 0
	v_mov_b32_e32 v129, 0
	s_add_i32 m0, s39, 0x0
	s_nop 0
	global_load_lds_dwordx4 v244, s[18:19]
	s_add_i32 m0, s39, 0x400
	s_nop 0
	global_load_lds_dwordx4 v245, s[18:19]
	s_add_i32 m0, s47, 0x0
	s_nop 0
	global_load_lds_dwordx4 v246, s[20:21]
	s_add_i32 m0, s47, 0x400
	s_nop 0
	global_load_lds_dwordx4 v247, s[20:21]
	s_add_i32 m0, s47, 0x800
	s_nop 0
	global_load_lds_dwordx4 v248, s[20:21]
	s_add_i32 m0, s47, 0xc00
	s_nop 0
	global_load_lds_dwordx4 v249, s[20:21]
	s_add_u32 s18, s18, 0x40000
	s_addc_u32 s19, s19, 0
	s_add_u32 s20, s20, 0x40000
	s_addc_u32 s21, s21, 0
	s_add_i32 m0, s39, 0xc000
	s_nop 0
	global_load_lds_dwordx4 v244, s[18:19]
	s_add_i32 m0, s39, 0xc400
	s_nop 0
	global_load_lds_dwordx4 v245, s[18:19]
	s_add_i32 m0, s47, 0xc000
	s_nop 0
	global_load_lds_dwordx4 v246, s[20:21]
	s_add_i32 m0, s47, 0xc400
	s_nop 0
	global_load_lds_dwordx4 v247, s[20:21]
	s_add_i32 m0, s47, 0xc800
	s_nop 0
	global_load_lds_dwordx4 v248, s[20:21]
	s_add_i32 m0, s47, 0xcc00
	s_nop 0
	global_load_lds_dwordx4 v249, s[20:21]
	s_add_u32 s18, s18, 0x40000
	s_addc_u32 s19, s19, 0
	s_add_u32 s20, s20, 0x40000
	s_addc_u32 s21, s21, 0
	s_waitcnt vmcnt(0)
	s_barrier
.Lam_loop:
	ds_read_b128 v[212:215], v228 offset:0
	ds_read_b128 v[216:219], v228 offset:8192
	ds_read_b128 v[220:223], v229 offset:0
	ds_read_b128 v[224:227], v229 offset:8192
	s_waitcnt lgkmcnt(2)
	v_mfma_f32_32x32x16_bf16 v[162:177], v[212:215], v[130:133], 0
	v_mfma_f32_32x32x16_bf16 v[178:193], v[216:219], v[130:133], 0
	ds_read_b128 v[212:215], v230 offset:0
	ds_read_b128 v[216:219], v230 offset:8192
	s_waitcnt lgkmcnt(2)
	v_mfma_f32_32x32x16_bf16 v[162:177], v[220:223], v[134:137], v[162:177]
	v_mfma_f32_32x32x16_bf16 v[178:193], v[224:227], v[134:137], v[178:193]
	ds_read_b128 v[220:223], v231 offset:0
	ds_read_b128 v[224:227], v231 offset:8192
	s_waitcnt lgkmcnt(2)
	v_mfma_f32_32x32x16_bf16 v[162:177], v[212:215], v[138:141], v[162:177]
	v_mfma_f32_32x32x16_bf16 v[178:193], v[216:219], v[138:141], v[178:193]
	ds_read_b128 v[212:215], v232 offset:0
	ds_read_b128 v[216:219], v232 offset:8192
	s_waitcnt lgkmcnt(2)
	v_mfma_f32_32x32x16_bf16 v[162:177], v[220:223], v[142:145], v[162:177]
	v_mfma_f32_32x32x16_bf16 v[178:193], v[224:227], v[142:145], v[178:193]
	ds_read_b128 v[220:223], v233 offset:0
	ds_read_b128 v[224:227], v233 offset:8192
	s_waitcnt lgkmcnt(2)
	v_mfma_f32_32x32x16_bf16 v[162:177], v[212:215], v[146:149], v[162:177]
	v_mfma_f32_32x32x16_bf16 v[178:193], v[216:219], v[146:149], v[178:193]
	ds_read_b128 v[212:215], v234 offset:0
	ds_read_b128 v[216:219], v234 offset:8192
	s_waitcnt lgkmcnt(2)
	v_mfma_f32_32x32x16_bf16 v[162:177], v[220:223], v[150:153], v[162:177]
	v_mfma_f32_32x32x16_bf16 v[178:193], v[224:227], v[150:153], v[178:193]
	ds_read_b128 v[220:223], v235 offset:0
	ds_read_b128 v[224:227], v235 offset:8192
	s_waitcnt lgkmcnt(2)
	v_mfma_f32_32x32x16_bf16 v[162:177], v[212:215], v[154:157], v[162:177]
	v_mfma_f32_32x32x16_bf16 v[178:193], v[216:219], v[154:157], v[178:193]
	s_waitcnt lgkmcnt(0)
	v_mfma_f32_32x32x16_bf16 v[162:177], v[220:223], v[158:161], v[162:177]
	v_mfma_f32_32x32x16_bf16 v[178:193], v[224:227], v[158:161], v[178:193]
	s_nop 7
	s_nop 4
	v_max_f32_e32 v240, v162, v163
	v_max3_f32 v240, v240, v164, v165
	v_max3_f32 v240, v240, v166, v167
	v_max3_f32 v240, v240, v168, v169
	v_max3_f32 v240, v240, v170, v171
	v_max3_f32 v240, v240, v172, v173
	v_max3_f32 v240, v240, v174, v175
	v_max3_f32 v240, v240, v176, v177
	v_max3_f32 v240, v240, v178, v179
	v_max3_f32 v240, v240, v180, v181
	v_max3_f32 v240, v240, v182, v183
	v_max3_f32 v240, v240, v184, v185
	v_max3_f32 v240, v240, v186, v187
	v_max3_f32 v240, v240, v188, v189
	v_max3_f32 v240, v240, v190, v191
	v_max3_f32 v240, v240, v192, v193
	v_mov_b32_e32 v241, v240
	s_nop 1
	v_permlane32_swap_b32_e32 v240, v241
	v_max_f32_e32 v240, v240, v241
	v_sub_f32_e32 v241, v240, v238
	v_cmp_ge_f32_e32 vcc, 0x42b504f3, v241
	s_nop 3
	s_cmp_eq_u64 vcc, exec
	s_cbranch_scc1 .Lam_keep_a
	v_max_f32_e32 v240, v238, v240
	v_sub_f32_e32 v241, v238, v240
	v_mul_f32_e32 v241, 0x3e0293ee, v241
	v_exp_f32_e32 v242, v241
	v_mov_b32_e32 v238, v240
	v_and_b32_e32 v240, 31, v96
	v_lshl_add_u32 v240, v240, 2, s50
	v_mul_f32_e32 v239, v239, v242
	ds_write_b32 v240, v242
	v_lshrrev_b32_e32 v240, 5, v96
	v_lshl_add_u32 v240, v240, 4, s50
	s_waitcnt lgkmcnt(0)
	ds_read_b128 v[212:215], v240 offset:0
	ds_read_b128 v[216:219], v240 offset:32
	ds_read_b128 v[220:223], v240 offset:64
	ds_read_b128 v[224:227], v240 offset:96
	s_waitcnt lgkmcnt(0)
	v_pk_mul_f32 v[0:1], v[0:1], v[212:213]
	v_pk_mul_f32 v[2:3], v[2:3], v[214:215]
	v_pk_mul_f32 v[4:5], v[4:5], v[216:217]
	v_pk_mul_f32 v[6:7], v[6:7], v[218:219]
	v_pk_mul_f32 v[8:9], v[8:9], v[220:221]
	v_pk_mul_f32 v[10:11], v[10:11], v[222:223]
	v_pk_mul_f32 v[12:13], v[12:13], v[224:225]
	v_pk_mul_f32 v[14:15], v[14:15], v[226:227]
	v_pk_mul_f32 v[16:17], v[16:17], v[212:213]
	v_pk_mul_f32 v[18:19], v[18:19], v[214:215]
	v_pk_mul_f32 v[20:21], v[20:21], v[216:217]
	v_pk_mul_f32 v[22:23], v[22:23], v[218:219]
	v_pk_mul_f32 v[24:25], v[24:25], v[220:221]
	v_pk_mul_f32 v[26:27], v[26:27], v[222:223]
	v_pk_mul_f32 v[28:29], v[28:29], v[224:225]
	v_pk_mul_f32 v[30:31], v[30:31], v[226:227]
	v_pk_mul_f32 v[32:33], v[32:33], v[212:213]
	v_pk_mul_f32 v[34:35], v[34:35], v[214:215]
	v_pk_mul_f32 v[36:37], v[36:37], v[216:217]
	v_pk_mul_f32 v[38:39], v[38:39], v[218:219]
	v_pk_mul_f32 v[40:41], v[40:41], v[220:221]
	v_pk_mul_f32 v[42:43], v[42:43], v[222:223]
	v_pk_mul_f32 v[44:45], v[44:45], v[224:225]
	v_pk_mul_f32 v[46:47], v[46:47], v[226:227]
	v_pk_mul_f32 v[48:49], v[48:49], v[212:213]
	v_pk_mul_f32 v[50:51], v[50:51], v[214:215]
	v_pk_mul_f32 v[52:53], v[52:53], v[216:217]
	v_pk_mul_f32 v[54:55], v[54:55], v[218:219]
	v_pk_mul_f32 v[56:57], v[56:57], v[220:221]
	v_pk_mul_f32 v[58:59], v[58:59], v[222:223]
	v_pk_mul_f32 v[60:61], v[60:61], v[224:225]
	v_pk_mul_f32 v[62:63], v[62:63], v[226:227]
	v_pk_mul_f32 v[64:65], v[64:65], v[212:213]
	v_pk_mul_f32 v[66:67], v[66:67], v[214:215]
	v_pk_mul_f32 v[68:69], v[68:69], v[216:217]
	v_pk_mul_f32 v[70:71], v[70:71], v[218:219]
	v_pk_mul_f32 v[72:73], v[72:73], v[220:221]
	v_pk_mul_f32 v[74:75], v[74:75], v[222:223]
	v_pk_mul_f32 v[76:77], v[76:77], v[224:225]
	v_pk_mul_f32 v[78:79], v[78:79], v[226:227]
	v_pk_mul_f32 v[80:81], v[80:81], v[212:213]
	v_pk_mul_f32 v[82:83], v[82:83], v[214:215]
	v_pk_mul_f32 v[84:85], v[84:85], v[216:217]
	v_pk_mul_f32 v[86:87], v[86:87], v[218:219]
	v_pk_mul_f32 v[88:89], v[88:89], v[220:221]
	v_pk_mul_f32 v[90:91], v[90:91], v[222:223]
	v_pk_mul_f32 v[92:93], v[92:93], v[224:225]
	v_pk_mul_f32 v[94:95], v[94:95], v[226:227]
	v_pk_mul_f32 v[98:99], v[98:99], v[212:213]
	v_pk_mul_f32 v[100:101], v[100:101], v[214:215]
	v_pk_mul_f32 v[102:103], v[102:103], v[216:217]
	v_pk_mul_f32 v[104:105], v[104:105], v[218:219]
	v_pk_mul_f32 v[106:107], v[106:107], v[220:221]
	v_pk_mul_f32 v[108:109], v[108:109], v[222:223]
	v_pk_mul_f32 v[110:111], v[110:111], v[224:225]
	v_pk_mul_f32 v[112:113], v[112:113], v[226:227]
	v_pk_mul_f32 v[114:115], v[114:115], v[212:213]
	v_pk_mul_f32 v[116:117], v[116:117], v[214:215]
	v_pk_mul_f32 v[118:119], v[118:119], v[216:217]
	v_pk_mul_f32 v[120:121], v[120:121], v[218:219]
	v_pk_mul_f32 v[122:123], v[122:123], v[220:221]
	v_pk_mul_f32 v[124:125], v[124:125], v[222:223]
	v_pk_mul_f32 v[126:127], v[126:127], v[224:225]
	v_pk_mul_f32 v[128:129], v[128:129], v[226:227]
.Lam_keep_a:
	v_mul_f32_e32 v243, 0xbe0293ee, v238
	v_fmamk_f32 v162, v162, 0x3e0293ee, v243
	v_fmamk_f32 v163, v163, 0x3e0293ee, v243
	v_fmamk_f32 v164, v164, 0x3e0293ee, v243
	v_fmamk_f32 v165, v165, 0x3e0293ee, v243
	v_fmamk_f32 v166, v166, 0x3e0293ee, v243
	v_fmamk_f32 v167, v167, 0x3e0293ee, v243
	v_fmamk_f32 v168, v168, 0x3e0293ee, v243
	v_fmamk_f32 v169, v169, 0x3e0293ee, v243
	v_fmamk_f32 v170, v170, 0x3e0293ee, v243
	v_fmamk_f32 v171, v171, 0x3e0293ee, v243
	v_fmamk_f32 v172, v172, 0x3e0293ee, v243
	v_fmamk_f32 v173, v173, 0x3e0293ee, v243
	v_fmamk_f32 v174, v174, 0x3e0293ee, v243
	v_fmamk_f32 v175, v175, 0x3e0293ee, v243
	v_fmamk_f32 v176, v176, 0x3e0293ee, v243
	v_fmamk_f32 v177, v177, 0x3e0293ee, v243
	v_fmamk_f32 v178, v178, 0x3e0293ee, v243
	v_fmamk_f32 v179, v179, 0x3e0293ee, v243
	v_fmamk_f32 v180, v180, 0x3e0293ee, v243
	v_fmamk_f32 v181, v181, 0x3e0293ee, v243
	v_fmamk_f32 v182, v182, 0x3e0293ee, v243
	v_fmamk_f32 v183, v183, 0x3e0293ee, v243
	v_fmamk_f32 v184, v184, 0x3e0293ee, v243
	v_fmamk_f32 v185, v185, 0x3e0293ee, v243
	v_fmamk_f32 v186, v186, 0x3e0293ee, v243
	v_fmamk_f32 v187, v187, 0x3e0293ee, v243
	v_fmamk_f32 v188, v188, 0x3e0293ee, v243
	v_fmamk_f32 v189, v189, 0x3e0293ee, v243
	v_fmamk_f32 v190, v190, 0x3e0293ee, v243
	v_fmamk_f32 v191, v191, 0x3e0293ee, v243
	v_fmamk_f32 v192, v192, 0x3e0293ee, v243
	v_fmamk_f32 v193, v193, 0x3e0293ee, v243
	v_exp_f32_e32 v162, v162
	v_exp_f32_e32 v163, v163
	v_exp_f32_e32 v164, v164
	v_exp_f32_e32 v165, v165
	v_exp_f32_e32 v166, v166
	v_exp_f32_e32 v167, v167
	v_exp_f32_e32 v168, v168
	v_exp_f32_e32 v169, v169
	v_exp_f32_e32 v170, v170
	v_exp_f32_e32 v171, v171
	v_exp_f32_e32 v172, v172
	v_exp_f32_e32 v173, v173
	v_exp_f32_e32 v174, v174
	v_exp_f32_e32 v175, v175
	v_exp_f32_e32 v176, v176
	v_exp_f32_e32 v177, v177
	v_exp_f32_e32 v178, v178
	v_exp_f32_e32 v179, v179
	v_exp_f32_e32 v180, v180
	v_exp_f32_e32 v181, v181
	v_exp_f32_e32 v182, v182
	v_exp_f32_e32 v183, v183
	v_exp_f32_e32 v184, v184
	v_exp_f32_e32 v185, v185
	v_exp_f32_e32 v186, v186
	v_exp_f32_e32 v187, v187
	v_exp_f32_e32 v188, v188
	v_exp_f32_e32 v189, v189
	v_exp_f32_e32 v190, v190
	v_exp_f32_e32 v191, v191
	v_exp_f32_e32 v192, v192
	v_exp_f32_e32 v193, v193
	v_add_f32_e32 v240, v162, v163
	v_add_f32_e32 v240, v240, v164
	v_add_f32_e32 v240, v240, v165
	v_add_f32_e32 v240, v240, v166
	v_add_f32_e32 v240, v240, v167
	v_add_f32_e32 v240, v240, v168
	v_add_f32_e32 v240, v240, v169
	v_add_f32_e32 v240, v240, v170
	v_add_f32_e32 v240, v240, v171
	v_add_f32_e32 v240, v240, v172
	v_add_f32_e32 v240, v240, v173
	v_add_f32_e32 v240, v240, v174
	v_add_f32_e32 v240, v240, v175
	v_add_f32_e32 v240, v240, v176
	v_add_f32_e32 v240, v240, v177
	v_add_f32_e32 v240, v240, v178
	v_add_f32_e32 v240, v240, v179
	v_add_f32_e32 v240, v240, v180
	v_add_f32_e32 v240, v240, v181
	v_add_f32_e32 v240, v240, v182
	v_add_f32_e32 v240, v240, v183
	v_add_f32_e32 v240, v240, v184
	v_add_f32_e32 v240, v240, v185
	v_add_f32_e32 v240, v240, v186
	v_add_f32_e32 v240, v240, v187
	v_add_f32_e32 v240, v240, v188
	v_add_f32_e32 v240, v240, v189
	v_add_f32_e32 v240, v240, v190
	v_add_f32_e32 v240, v240, v191
	v_add_f32_e32 v240, v240, v192
	v_add_f32_e32 v240, v240, v193
	v_mov_b32_e32 v241, v240
	v_cvt_pk_bf16_f32 v196, v162, v163
	v_cvt_pk_bf16_f32 v197, v164, v165
	v_cvt_pk_bf16_f32 v198, v166, v167
	v_cvt_pk_bf16_f32 v199, v168, v169
	v_cvt_pk_bf16_f32 v200, v170, v171
	v_cvt_pk_bf16_f32 v201, v172, v173
	v_cvt_pk_bf16_f32 v202, v174, v175
	v_cvt_pk_bf16_f32 v203, v176, v177
	v_cvt_pk_bf16_f32 v204, v178, v179
	v_cvt_pk_bf16_f32 v205, v180, v181
	v_cvt_pk_bf16_f32 v206, v182, v183
	v_cvt_pk_bf16_f32 v207, v184, v185
	v_cvt_pk_bf16_f32 v208, v186, v187
	v_cvt_pk_bf16_f32 v209, v188, v189
	v_cvt_pk_bf16_f32 v210, v190, v191
	v_cvt_pk_bf16_f32 v211, v192, v193
	s_nop 1
	v_permlane32_swap_b32_e32 v240, v241
	v_permlane32_swap_b32_e32 v196, v198
	v_permlane32_swap_b32_e32 v197, v199
	v_permlane32_swap_b32_e32 v200, v202
	v_permlane32_swap_b32_e32 v201, v203
	v_permlane32_swap_b32_e32 v204, v206
	v_permlane32_swap_b32_e32 v205, v207
	v_permlane32_swap_b32_e32 v208, v210
	v_permlane32_swap_b32_e32 v209, v211
	v_add_f32_e32 v240, v240, v241
	v_add_f32_e32 v239, v239, v240
	ds_read_b64_tr_b16 v[162:163], v236 offset:0
	ds_read_b64_tr_b16 v[164:165], v236 offset:4096
	ds_read_b64_tr_b16 v[166:167], v236 offset:8192
	ds_read_b64_tr_b16 v[168:169], v236 offset:12288
	ds_read_b64_tr_b16 v[170:171], v236 offset:16384
	ds_read_b64_tr_b16 v[172:173], v236 offset:20480
	ds_read_b64_tr_b16 v[174:175], v236 offset:24576
	ds_read_b64_tr_b16 v[176:177], v236 offset:28672
	ds_read_b64_tr_b16 v[178:179], v236 offset:512
	ds_read_b64_tr_b16 v[180:181], v236 offset:4608
	ds_read_b64_tr_b16 v[182:183], v236 offset:8704
	ds_read_b64_tr_b16 v[184:185], v236 offset:12800
	ds_read_b64_tr_b16 v[186:187], v236 offset:16896
	ds_read_b64_tr_b16 v[188:189], v236 offset:20992
	ds_read_b64_tr_b16 v[190:191], v236 offset:25088
	ds_read_b64_tr_b16 v[192:193], v236 offset:29184
	s_waitcnt lgkmcnt(8)
	v_mfma_f32_32x32x16_bf16 v[0:15], v[196:199], v[162:165], v[0:15]
	v_mfma_f32_32x32x16_bf16 v[0:15], v[200:203], v[166:169], v[0:15]
	v_mfma_f32_32x32x16_bf16 v[0:15], v[204:207], v[170:173], v[0:15]
	v_mfma_f32_32x32x16_bf16 v[0:15], v[208:211], v[174:177], v[0:15]
	ds_read_b64_tr_b16 v[162:163], v236 offset:1024
	ds_read_b64_tr_b16 v[164:165], v236 offset:5120
	ds_read_b64_tr_b16 v[166:167], v236 offset:9216
	ds_read_b64_tr_b16 v[168:169], v236 offset:13312
	ds_read_b64_tr_b16 v[170:171], v236 offset:17408
	ds_read_b64_tr_b16 v[172:173], v236 offset:21504
	ds_read_b64_tr_b16 v[174:175], v236 offset:25600
	ds_read_b64_tr_b16 v[176:177], v236 offset:29696
	s_waitcnt lgkmcnt(8)
	v_mfma_f32_32x32x16_bf16 v[16:31], v[196:199], v[178:181], v[16:31]
	v_mfma_f32_32x32x16_bf16 v[16:31], v[200:203], v[182:185], v[16:31]
	v_mfma_f32_32x32x16_bf16 v[16:31], v[204:207], v[186:189], v[16:31]
	v_mfma_f32_32x32x16_bf16 v[16:31], v[208:211], v[190:193], v[16:31]
	ds_read_b64_tr_b16 v[178:179], v236 offset:1536
	ds_read_b64_tr_b16 v[180:181], v236 offset:5632
	ds_read_b64_tr_b16 v[182:183], v236 offset:9728
	ds_read_b64_tr_b16 v[184:185], v236 offset:13824
	ds_read_b64_tr_b16 v[186:187], v236 offset:17920
	ds_read_b64_tr_b16 v[188:189], v236 offset:22016
	ds_read_b64_tr_b16 v[190:191], v236 offset:26112
	ds_read_b64_tr_b16 v[192:193], v236 offset:30208
	s_waitcnt lgkmcnt(8)
	v_mfma_f32_32x32x16_bf16 v[32:47], v[196:199], v[162:165], v[32:47]
	v_mfma_f32_32x32x16_bf16 v[32:47], v[200:203], v[166:169], v[32:47]
	v_mfma_f32_32x32x16_bf16 v[32:47], v[204:207], v[170:173], v[32:47]
	v_mfma_f32_32x32x16_bf16 v[32:47], v[208:211], v[174:177], v[32:47]
	ds_read_b64_tr_b16 v[162:163], v236 offset:2048
	ds_read_b64_tr_b16 v[164:165], v236 offset:6144
	ds_read_b64_tr_b16 v[166:167], v236 offset:10240
	ds_read_b64_tr_b16 v[168:169], v236 offset:14336
	ds_read_b64_tr_b16 v[170:171], v236 offset:18432
	ds_read_b64_tr_b16 v[172:173], v236 offset:22528
	ds_read_b64_tr_b16 v[174:175], v236 offset:26624
	ds_read_b64_tr_b16 v[176:177], v236 offset:30720
	s_waitcnt lgkmcnt(8)
	v_mfma_f32_32x32x16_bf16 v[48:63], v[196:199], v[178:181], v[48:63]
	v_mfma_f32_32x32x16_bf16 v[48:63], v[200:203], v[182:185], v[48:63]
	v_mfma_f32_32x32x16_bf16 v[48:63], v[204:207], v[186:189], v[48:63]
	v_mfma_f32_32x32x16_bf16 v[48:63], v[208:211], v[190:193], v[48:63]
	ds_read_b64_tr_b16 v[178:179], v236 offset:2560
	ds_read_b64_tr_b16 v[180:181], v236 offset:6656
	ds_read_b64_tr_b16 v[182:183], v236 offset:10752
	ds_read_b64_tr_b16 v[184:185], v236 offset:14848
	ds_read_b64_tr_b16 v[186:187], v236 offset:18944
	ds_read_b64_tr_b16 v[188:189], v236 offset:23040
	ds_read_b64_tr_b16 v[190:191], v236 offset:27136
	ds_read_b64_tr_b16 v[192:193], v236 offset:31232
	s_waitcnt lgkmcnt(8)
	v_mfma_f32_32x32x16_bf16 v[64:79], v[196:199], v[162:165], v[64:79]
	v_mfma_f32_32x32x16_bf16 v[64:79], v[200:203], v[166:169], v[64:79]
	v_mfma_f32_32x32x16_bf16 v[64:79], v[204:207], v[170:173], v[64:79]
	v_mfma_f32_32x32x16_bf16 v[64:79], v[208:211], v[174:177], v[64:79]
	ds_read_b64_tr_b16 v[162:163], v236 offset:3072
	ds_read_b64_tr_b16 v[164:165], v236 offset:7168
	ds_read_b64_tr_b16 v[166:167], v236 offset:11264
	ds_read_b64_tr_b16 v[168:169], v236 offset:15360
	ds_read_b64_tr_b16 v[170:171], v236 offset:19456
	ds_read_b64_tr_b16 v[172:173], v236 offset:23552
	ds_read_b64_tr_b16 v[174:175], v236 offset:27648
	ds_read_b64_tr_b16 v[176:177], v236 offset:31744
	s_waitcnt lgkmcnt(8)
	v_mfma_f32_32x32x16_bf16 v[80:95], v[196:199], v[178:181], v[80:95]
	v_mfma_f32_32x32x16_bf16 v[80:95], v[200:203], v[182:185], v[80:95]
	v_mfma_f32_32x32x16_bf16 v[80:95], v[204:207], v[186:189], v[80:95]
	v_mfma_f32_32x32x16_bf16 v[80:95], v[208:211], v[190:193], v[80:95]
	ds_read_b64_tr_b16 v[178:179], v236 offset:3584
	ds_read_b64_tr_b16 v[180:181], v236 offset:7680
	ds_read_b64_tr_b16 v[182:183], v236 offset:11776
	ds_read_b64_tr_b16 v[184:185], v236 offset:15872
	ds_read_b64_tr_b16 v[186:187], v236 offset:19968
	ds_read_b64_tr_b16 v[188:189], v236 offset:24064
	ds_read_b64_tr_b16 v[190:191], v236 offset:28160
	ds_read_b64_tr_b16 v[192:193], v236 offset:32256
	s_waitcnt lgkmcnt(8)
	v_mfma_f32_32x32x16_bf16 v[98:113], v[196:199], v[162:165], v[98:113]
	v_mfma_f32_32x32x16_bf16 v[98:113], v[200:203], v[166:169], v[98:113]
	v_mfma_f32_32x32x16_bf16 v[98:113], v[204:207], v[170:173], v[98:113]
	v_mfma_f32_32x32x16_bf16 v[98:113], v[208:211], v[174:177], v[98:113]
	s_waitcnt lgkmcnt(0)
	v_mfma_f32_32x32x16_bf16 v[114:129], v[196:199], v[178:181], v[114:129]
	v_mfma_f32_32x32x16_bf16 v[114:129], v[200:203], v[182:185], v[114:129]
	v_mfma_f32_32x32x16_bf16 v[114:129], v[204:207], v[186:189], v[114:129]
	v_mfma_f32_32x32x16_bf16 v[114:129], v[208:211], v[190:193], v[114:129]
	s_waitcnt vmcnt(0)
	s_barrier
	s_cmp_le_u32 s13, 2
	s_cbranch_scc1 .Lam_nodma_a
	s_add_i32 m0, s39, 0x0
	s_nop 0
	global_load_lds_dwordx4 v244, s[18:19]
	s_add_i32 m0, s39, 0x400
	s_nop 0
	global_load_lds_dwordx4 v245, s[18:19]
	s_add_i32 m0, s47, 0x0
	s_nop 0
	global_load_lds_dwordx4 v246, s[20:21]
	s_add_i32 m0, s47, 0x400
	s_nop 0
	global_load_lds_dwordx4 v247, s[20:21]
	s_add_i32 m0, s47, 0x800
	s_nop 0
	global_load_lds_dwordx4 v248, s[20:21]
	s_add_i32 m0, s47, 0xc00
	s_nop 0
	global_load_lds_dwordx4 v249, s[20:21]
	s_add_u32 s18, s18, 0x40000
	s_addc_u32 s19, s19, 0
	s_add_u32 s20, s20, 0x40000
	s_addc_u32 s21, s21, 0
.Lam_nodma_a:
	ds_read_b128 v[212:215], v228 offset:49152
	ds_read_b128 v[216:219], v228 offset:57344
	ds_read_b128 v[220:223], v229 offset:49152
	ds_read_b128 v[224:227], v229 offset:57344
	s_waitcnt lgkmcnt(2)
	v_mfma_f32_32x32x16_bf16 v[162:177], v[212:215], v[130:133], 0
	v_mfma_f32_32x32x16_bf16 v[178:193], v[216:219], v[130:133], 0
	ds_read_b128 v[212:215], v230 offset:49152
	ds_read_b128 v[216:219], v230 offset:57344
	s_waitcnt lgkmcnt(2)
	v_mfma_f32_32x32x16_bf16 v[162:177], v[220:223], v[134:137], v[162:177]
	v_mfma_f32_32x32x16_bf16 v[178:193], v[224:227], v[134:137], v[178:193]
	ds_read_b128 v[220:223], v231 offset:49152
	ds_read_b128 v[224:227], v231 offset:57344
	s_waitcnt lgkmcnt(2)
	v_mfma_f32_32x32x16_bf16 v[162:177], v[212:215], v[138:141], v[162:177]
	v_mfma_f32_32x32x16_bf16 v[178:193], v[216:219], v[138:141], v[178:193]
	ds_read_b128 v[212:215], v232 offset:49152
	ds_read_b128 v[216:219], v232 offset:57344
	s_waitcnt lgkmcnt(2)
	v_mfma_f32_32x32x16_bf16 v[162:177], v[220:223], v[142:145], v[162:177]
	v_mfma_f32_32x32x16_bf16 v[178:193], v[224:227], v[142:145], v[178:193]
	ds_read_b128 v[220:223], v233 offset:49152
	ds_read_b128 v[224:227], v233 offset:57344
	s_waitcnt lgkmcnt(2)
	v_mfma_f32_32x32x16_bf16 v[162:177], v[212:215], v[146:149], v[162:177]
	v_mfma_f32_32x32x16_bf16 v[178:193], v[216:219], v[146:149], v[178:193]
	ds_read_b128 v[212:215], v234 offset:49152
	ds_read_b128 v[216:219], v234 offset:57344
	s_waitcnt lgkmcnt(2)
	v_mfma_f32_32x32x16_bf16 v[162:177], v[220:223], v[150:153], v[162:177]
	v_mfma_f32_32x32x16_bf16 v[178:193], v[224:227], v[150:153], v[178:193]
	ds_read_b128 v[220:223], v235 offset:49152
	ds_read_b128 v[224:227], v235 offset:57344
	s_waitcnt lgkmcnt(2)
	v_mfma_f32_32x32x16_bf16 v[162:177], v[212:215], v[154:157], v[162:177]
	v_mfma_f32_32x32x16_bf16 v[178:193], v[216:219], v[154:157], v[178:193]
	s_waitcnt lgkmcnt(0)
	v_mfma_f32_32x32x16_bf16 v[162:177], v[220:223], v[158:161], v[162:177]
	v_mfma_f32_32x32x16_bf16 v[178:193], v[224:227], v[158:161], v[178:193]
	s_nop 7
	s_nop 4
	v_max_f32_e32 v240, v162, v163
	v_max3_f32 v240, v240, v164, v165
	v_max3_f32 v240, v240, v166, v167
	v_max3_f32 v240, v240, v168, v169
	v_max3_f32 v240, v240, v170, v171
	v_max3_f32 v240, v240, v172, v173
	v_max3_f32 v240, v240, v174, v175
	v_max3_f32 v240, v240, v176, v177
	v_max3_f32 v240, v240, v178, v179
	v_max3_f32 v240, v240, v180, v181
	v_max3_f32 v240, v240, v182, v183
	v_max3_f32 v240, v240, v184, v185
	v_max3_f32 v240, v240, v186, v187
	v_max3_f32 v240, v240, v188, v189
	v_max3_f32 v240, v240, v190, v191
	v_max3_f32 v240, v240, v192, v193
	v_mov_b32_e32 v241, v240
	s_nop 1
	v_permlane32_swap_b32_e32 v240, v241
	v_max_f32_e32 v240, v240, v241
	v_sub_f32_e32 v241, v240, v238
	v_cmp_ge_f32_e32 vcc, 0x42b504f3, v241
	s_nop 3
	s_cmp_eq_u64 vcc, exec
	s_cbranch_scc1 .Lam_keep_b
	v_max_f32_e32 v240, v238, v240
	v_sub_f32_e32 v241, v238, v240
	v_mul_f32_e32 v241, 0x3e0293ee, v241
	v_exp_f32_e32 v242, v241
	v_mov_b32_e32 v238, v240
	v_and_b32_e32 v240, 31, v96
	v_lshl_add_u32 v240, v240, 2, s50
	v_mul_f32_e32 v239, v239, v242
	ds_write_b32 v240, v242
	v_lshrrev_b32_e32 v240, 5, v96
	v_lshl_add_u32 v240, v240, 4, s50
	s_waitcnt lgkmcnt(0)
	ds_read_b128 v[212:215], v240 offset:0
	ds_read_b128 v[216:219], v240 offset:32
	ds_read_b128 v[220:223], v240 offset:64
	ds_read_b128 v[224:227], v240 offset:96
	s_waitcnt lgkmcnt(0)
	v_pk_mul_f32 v[0:1], v[0:1], v[212:213]
	v_pk_mul_f32 v[2:3], v[2:3], v[214:215]
	v_pk_mul_f32 v[4:5], v[4:5], v[216:217]
	v_pk_mul_f32 v[6:7], v[6:7], v[218:219]
	v_pk_mul_f32 v[8:9], v[8:9], v[220:221]
	v_pk_mul_f32 v[10:11], v[10:11], v[222:223]
	v_pk_mul_f32 v[12:13], v[12:13], v[224:225]
	v_pk_mul_f32 v[14:15], v[14:15], v[226:227]
	v_pk_mul_f32 v[16:17], v[16:17], v[212:213]
	v_pk_mul_f32 v[18:19], v[18:19], v[214:215]
	v_pk_mul_f32 v[20:21], v[20:21], v[216:217]
	v_pk_mul_f32 v[22:23], v[22:23], v[218:219]
	v_pk_mul_f32 v[24:25], v[24:25], v[220:221]
	v_pk_mul_f32 v[26:27], v[26:27], v[222:223]
	v_pk_mul_f32 v[28:29], v[28:29], v[224:225]
	v_pk_mul_f32 v[30:31], v[30:31], v[226:227]
	v_pk_mul_f32 v[32:33], v[32:33], v[212:213]
	v_pk_mul_f32 v[34:35], v[34:35], v[214:215]
	v_pk_mul_f32 v[36:37], v[36:37], v[216:217]
	v_pk_mul_f32 v[38:39], v[38:39], v[218:219]
	v_pk_mul_f32 v[40:41], v[40:41], v[220:221]
	v_pk_mul_f32 v[42:43], v[42:43], v[222:223]
	v_pk_mul_f32 v[44:45], v[44:45], v[224:225]
	v_pk_mul_f32 v[46:47], v[46:47], v[226:227]
	v_pk_mul_f32 v[48:49], v[48:49], v[212:213]
	v_pk_mul_f32 v[50:51], v[50:51], v[214:215]
	v_pk_mul_f32 v[52:53], v[52:53], v[216:217]
	v_pk_mul_f32 v[54:55], v[54:55], v[218:219]
	v_pk_mul_f32 v[56:57], v[56:57], v[220:221]
	v_pk_mul_f32 v[58:59], v[58:59], v[222:223]
	v_pk_mul_f32 v[60:61], v[60:61], v[224:225]
	v_pk_mul_f32 v[62:63], v[62:63], v[226:227]
	v_pk_mul_f32 v[64:65], v[64:65], v[212:213]
	v_pk_mul_f32 v[66:67], v[66:67], v[214:215]
	v_pk_mul_f32 v[68:69], v[68:69], v[216:217]
	v_pk_mul_f32 v[70:71], v[70:71], v[218:219]
	v_pk_mul_f32 v[72:73], v[72:73], v[220:221]
	v_pk_mul_f32 v[74:75], v[74:75], v[222:223]
	v_pk_mul_f32 v[76:77], v[76:77], v[224:225]
	v_pk_mul_f32 v[78:79], v[78:79], v[226:227]
	v_pk_mul_f32 v[80:81], v[80:81], v[212:213]
	v_pk_mul_f32 v[82:83], v[82:83], v[214:215]
	v_pk_mul_f32 v[84:85], v[84:85], v[216:217]
	v_pk_mul_f32 v[86:87], v[86:87], v[218:219]
	v_pk_mul_f32 v[88:89], v[88:89], v[220:221]
	v_pk_mul_f32 v[90:91], v[90:91], v[222:223]
	v_pk_mul_f32 v[92:93], v[92:93], v[224:225]
	v_pk_mul_f32 v[94:95], v[94:95], v[226:227]
	v_pk_mul_f32 v[98:99], v[98:99], v[212:213]
	v_pk_mul_f32 v[100:101], v[100:101], v[214:215]
	v_pk_mul_f32 v[102:103], v[102:103], v[216:217]
	v_pk_mul_f32 v[104:105], v[104:105], v[218:219]
	v_pk_mul_f32 v[106:107], v[106:107], v[220:221]
	v_pk_mul_f32 v[108:109], v[108:109], v[222:223]
	v_pk_mul_f32 v[110:111], v[110:111], v[224:225]
	v_pk_mul_f32 v[112:113], v[112:113], v[226:227]
	v_pk_mul_f32 v[114:115], v[114:115], v[212:213]
	v_pk_mul_f32 v[116:117], v[116:117], v[214:215]
	v_pk_mul_f32 v[118:119], v[118:119], v[216:217]
	v_pk_mul_f32 v[120:121], v[120:121], v[218:219]
	v_pk_mul_f32 v[122:123], v[122:123], v[220:221]
	v_pk_mul_f32 v[124:125], v[124:125], v[222:223]
	v_pk_mul_f32 v[126:127], v[126:127], v[224:225]
	v_pk_mul_f32 v[128:129], v[128:129], v[226:227]
.Lam_keep_b:
	v_mul_f32_e32 v243, 0xbe0293ee, v238
	v_fmamk_f32 v162, v162, 0x3e0293ee, v243
	v_fmamk_f32 v163, v163, 0x3e0293ee, v243
	v_fmamk_f32 v164, v164, 0x3e0293ee, v243
	v_fmamk_f32 v165, v165, 0x3e0293ee, v243
	v_fmamk_f32 v166, v166, 0x3e0293ee, v243
	v_fmamk_f32 v167, v167, 0x3e0293ee, v243
	v_fmamk_f32 v168, v168, 0x3e0293ee, v243
	v_fmamk_f32 v169, v169, 0x3e0293ee, v243
	v_fmamk_f32 v170, v170, 0x3e0293ee, v243
	v_fmamk_f32 v171, v171, 0x3e0293ee, v243
	v_fmamk_f32 v172, v172, 0x3e0293ee, v243
	v_fmamk_f32 v173, v173, 0x3e0293ee, v243
	v_fmamk_f32 v174, v174, 0x3e0293ee, v243
	v_fmamk_f32 v175, v175, 0x3e0293ee, v243
	v_fmamk_f32 v176, v176, 0x3e0293ee, v243
	v_fmamk_f32 v177, v177, 0x3e0293ee, v243
	v_fmamk_f32 v178, v178, 0x3e0293ee, v243
	v_fmamk_f32 v179, v179, 0x3e0293ee, v243
	v_fmamk_f32 v180, v180, 0x3e0293ee, v243
	v_fmamk_f32 v181, v181, 0x3e0293ee, v243
	v_fmamk_f32 v182, v182, 0x3e0293ee, v243
	v_fmamk_f32 v183, v183, 0x3e0293ee, v243
	v_fmamk_f32 v184, v184, 0x3e0293ee, v243
	v_fmamk_f32 v185, v185, 0x3e0293ee, v243
	v_fmamk_f32 v186, v186, 0x3e0293ee, v243
	v_fmamk_f32 v187, v187, 0x3e0293ee, v243
	v_fmamk_f32 v188, v188, 0x3e0293ee, v243
	v_fmamk_f32 v189, v189, 0x3e0293ee, v243
	v_fmamk_f32 v190, v190, 0x3e0293ee, v243
	v_fmamk_f32 v191, v191, 0x3e0293ee, v243
	v_fmamk_f32 v192, v192, 0x3e0293ee, v243
	v_fmamk_f32 v193, v193, 0x3e0293ee, v243
	v_exp_f32_e32 v162, v162
	v_exp_f32_e32 v163, v163
	v_exp_f32_e32 v164, v164
	v_exp_f32_e32 v165, v165
	v_exp_f32_e32 v166, v166
	v_exp_f32_e32 v167, v167
	v_exp_f32_e32 v168, v168
	v_exp_f32_e32 v169, v169
	v_exp_f32_e32 v170, v170
	v_exp_f32_e32 v171, v171
	v_exp_f32_e32 v172, v172
	v_exp_f32_e32 v173, v173
	v_exp_f32_e32 v174, v174
	v_exp_f32_e32 v175, v175
	v_exp_f32_e32 v176, v176
	v_exp_f32_e32 v177, v177
	v_exp_f32_e32 v178, v178
	v_exp_f32_e32 v179, v179
	v_exp_f32_e32 v180, v180
	v_exp_f32_e32 v181, v181
	v_exp_f32_e32 v182, v182
	v_exp_f32_e32 v183, v183
	v_exp_f32_e32 v184, v184
	v_exp_f32_e32 v185, v185
	v_exp_f32_e32 v186, v186
	v_exp_f32_e32 v187, v187
	v_exp_f32_e32 v188, v188
	v_exp_f32_e32 v189, v189
	v_exp_f32_e32 v190, v190
	v_exp_f32_e32 v191, v191
	v_exp_f32_e32 v192, v192
	v_exp_f32_e32 v193, v193
	v_add_f32_e32 v240, v162, v163
	v_add_f32_e32 v240, v240, v164
	v_add_f32_e32 v240, v240, v165
	v_add_f32_e32 v240, v240, v166
	v_add_f32_e32 v240, v240, v167
	v_add_f32_e32 v240, v240, v168
	v_add_f32_e32 v240, v240, v169
	v_add_f32_e32 v240, v240, v170
	v_add_f32_e32 v240, v240, v171
	v_add_f32_e32 v240, v240, v172
	v_add_f32_e32 v240, v240, v173
	v_add_f32_e32 v240, v240, v174
	v_add_f32_e32 v240, v240, v175
	v_add_f32_e32 v240, v240, v176
	v_add_f32_e32 v240, v240, v177
	v_add_f32_e32 v240, v240, v178
	v_add_f32_e32 v240, v240, v179
	v_add_f32_e32 v240, v240, v180
	v_add_f32_e32 v240, v240, v181
	v_add_f32_e32 v240, v240, v182
	v_add_f32_e32 v240, v240, v183
	v_add_f32_e32 v240, v240, v184
	v_add_f32_e32 v240, v240, v185
	v_add_f32_e32 v240, v240, v186
	v_add_f32_e32 v240, v240, v187
	v_add_f32_e32 v240, v240, v188
	v_add_f32_e32 v240, v240, v189
	v_add_f32_e32 v240, v240, v190
	v_add_f32_e32 v240, v240, v191
	v_add_f32_e32 v240, v240, v192
	v_add_f32_e32 v240, v240, v193
	v_mov_b32_e32 v241, v240
	v_cvt_pk_bf16_f32 v196, v162, v163
	v_cvt_pk_bf16_f32 v197, v164, v165
	v_cvt_pk_bf16_f32 v198, v166, v167
	v_cvt_pk_bf16_f32 v199, v168, v169
	v_cvt_pk_bf16_f32 v200, v170, v171
	v_cvt_pk_bf16_f32 v201, v172, v173
	v_cvt_pk_bf16_f32 v202, v174, v175
	v_cvt_pk_bf16_f32 v203, v176, v177
	v_cvt_pk_bf16_f32 v204, v178, v179
	v_cvt_pk_bf16_f32 v205, v180, v181
	v_cvt_pk_bf16_f32 v206, v182, v183
	v_cvt_pk_bf16_f32 v207, v184, v185
	v_cvt_pk_bf16_f32 v208, v186, v187
	v_cvt_pk_bf16_f32 v209, v188, v189
	v_cvt_pk_bf16_f32 v210, v190, v191
	v_cvt_pk_bf16_f32 v211, v192, v193
	s_nop 1
	v_permlane32_swap_b32_e32 v240, v241
	v_permlane32_swap_b32_e32 v196, v198
	v_permlane32_swap_b32_e32 v197, v199
	v_permlane32_swap_b32_e32 v200, v202
	v_permlane32_swap_b32_e32 v201, v203
	v_permlane32_swap_b32_e32 v204, v206
	v_permlane32_swap_b32_e32 v205, v207
	v_permlane32_swap_b32_e32 v208, v210
	v_permlane32_swap_b32_e32 v209, v211
	v_add_f32_e32 v240, v240, v241
	v_add_f32_e32 v239, v239, v240
	ds_read_b64_tr_b16 v[162:163], v237 offset:0
	ds_read_b64_tr_b16 v[164:165], v237 offset:4096
	ds_read_b64_tr_b16 v[166:167], v237 offset:8192
	ds_read_b64_tr_b16 v[168:169], v237 offset:12288
	ds_read_b64_tr_b16 v[170:171], v237 offset:16384
	ds_read_b64_tr_b16 v[172:173], v237 offset:20480
	ds_read_b64_tr_b16 v[174:175], v237 offset:24576
	ds_read_b64_tr_b16 v[176:177], v237 offset:28672
	ds_read_b64_tr_b16 v[178:179], v237 offset:512
	ds_read_b64_tr_b16 v[180:181], v237 offset:4608
	ds_read_b64_tr_b16 v[182:183], v237 offset:8704
	ds_read_b64_tr_b16 v[184:185], v237 offset:12800
	ds_read_b64_tr_b16 v[186:187], v237 offset:16896
	ds_read_b64_tr_b16 v[188:189], v237 offset:20992
	ds_read_b64_tr_b16 v[190:191], v237 offset:25088
	ds_read_b64_tr_b16 v[192:193], v237 offset:29184
	s_waitcnt lgkmcnt(8)
	v_mfma_f32_32x32x16_bf16 v[0:15], v[196:199], v[162:165], v[0:15]
	v_mfma_f32_32x32x16_bf16 v[0:15], v[200:203], v[166:169], v[0:15]
	v_mfma_f32_32x32x16_bf16 v[0:15], v[204:207], v[170:173], v[0:15]
	v_mfma_f32_32x32x16_bf16 v[0:15], v[208:211], v[174:177], v[0:15]
	ds_read_b64_tr_b16 v[162:163], v237 offset:1024
	ds_read_b64_tr_b16 v[164:165], v237 offset:5120
	ds_read_b64_tr_b16 v[166:167], v237 offset:9216
	ds_read_b64_tr_b16 v[168:169], v237 offset:13312
	ds_read_b64_tr_b16 v[170:171], v237 offset:17408
	ds_read_b64_tr_b16 v[172:173], v237 offset:21504
	ds_read_b64_tr_b16 v[174:175], v237 offset:25600
	ds_read_b64_tr_b16 v[176:177], v237 offset:29696
	s_waitcnt lgkmcnt(8)
	v_mfma_f32_32x32x16_bf16 v[16:31], v[196:199], v[178:181], v[16:31]
	v_mfma_f32_32x32x16_bf16 v[16:31], v[200:203], v[182:185], v[16:31]
	v_mfma_f32_32x32x16_bf16 v[16:31], v[204:207], v[186:189], v[16:31]
	v_mfma_f32_32x32x16_bf16 v[16:31], v[208:211], v[190:193], v[16:31]
	ds_read_b64_tr_b16 v[178:179], v237 offset:1536
	ds_read_b64_tr_b16 v[180:181], v237 offset:5632
	ds_read_b64_tr_b16 v[182:183], v237 offset:9728
	ds_read_b64_tr_b16 v[184:185], v237 offset:13824
	ds_read_b64_tr_b16 v[186:187], v237 offset:17920
	ds_read_b64_tr_b16 v[188:189], v237 offset:22016
	ds_read_b64_tr_b16 v[190:191], v237 offset:26112
	ds_read_b64_tr_b16 v[192:193], v237 offset:30208
	s_waitcnt lgkmcnt(8)
	v_mfma_f32_32x32x16_bf16 v[32:47], v[196:199], v[162:165], v[32:47]
	v_mfma_f32_32x32x16_bf16 v[32:47], v[200:203], v[166:169], v[32:47]
	v_mfma_f32_32x32x16_bf16 v[32:47], v[204:207], v[170:173], v[32:47]
	v_mfma_f32_32x32x16_bf16 v[32:47], v[208:211], v[174:177], v[32:47]
	ds_read_b64_tr_b16 v[162:163], v237 offset:2048
	ds_read_b64_tr_b16 v[164:165], v237 offset:6144
	ds_read_b64_tr_b16 v[166:167], v237 offset:10240
	ds_read_b64_tr_b16 v[168:169], v237 offset:14336
	ds_read_b64_tr_b16 v[170:171], v237 offset:18432
	ds_read_b64_tr_b16 v[172:173], v237 offset:22528
	ds_read_b64_tr_b16 v[174:175], v237 offset:26624
	ds_read_b64_tr_b16 v[176:177], v237 offset:30720
	s_waitcnt lgkmcnt(8)
	v_mfma_f32_32x32x16_bf16 v[48:63], v[196:199], v[178:181], v[48:63]
	v_mfma_f32_32x32x16_bf16 v[48:63], v[200:203], v[182:185], v[48:63]
	v_mfma_f32_32x32x16_bf16 v[48:63], v[204:207], v[186:189], v[48:63]
	v_mfma_f32_32x32x16_bf16 v[48:63], v[208:211], v[190:193], v[48:63]
	ds_read_b64_tr_b16 v[178:179], v237 offset:2560
	ds_read_b64_tr_b16 v[180:181], v237 offset:6656
	ds_read_b64_tr_b16 v[182:183], v237 offset:10752
	ds_read_b64_tr_b16 v[184:185], v237 offset:14848
	ds_read_b64_tr_b16 v[186:187], v237 offset:18944
	ds_read_b64_tr_b16 v[188:189], v237 offset:23040
	ds_read_b64_tr_b16 v[190:191], v237 offset:27136
	ds_read_b64_tr_b16 v[192:193], v237 offset:31232
	s_waitcnt lgkmcnt(8)
	v_mfma_f32_32x32x16_bf16 v[64:79], v[196:199], v[162:165], v[64:79]
	v_mfma_f32_32x32x16_bf16 v[64:79], v[200:203], v[166:169], v[64:79]
	v_mfma_f32_32x32x16_bf16 v[64:79], v[204:207], v[170:173], v[64:79]
	v_mfma_f32_32x32x16_bf16 v[64:79], v[208:211], v[174:177], v[64:79]
	ds_read_b64_tr_b16 v[162:163], v237 offset:3072
	ds_read_b64_tr_b16 v[164:165], v237 offset:7168
	ds_read_b64_tr_b16 v[166:167], v237 offset:11264
	ds_read_b64_tr_b16 v[168:169], v237 offset:15360
	ds_read_b64_tr_b16 v[170:171], v237 offset:19456
	ds_read_b64_tr_b16 v[172:173], v237 offset:23552
	ds_read_b64_tr_b16 v[174:175], v237 offset:27648
	ds_read_b64_tr_b16 v[176:177], v237 offset:31744
	s_waitcnt lgkmcnt(8)
	v_mfma_f32_32x32x16_bf16 v[80:95], v[196:199], v[178:181], v[80:95]
	v_mfma_f32_32x32x16_bf16 v[80:95], v[200:203], v[182:185], v[80:95]
	v_mfma_f32_32x32x16_bf16 v[80:95], v[204:207], v[186:189], v[80:95]
	v_mfma_f32_32x32x16_bf16 v[80:95], v[208:211], v[190:193], v[80:95]
	ds_read_b64_tr_b16 v[178:179], v237 offset:3584
	ds_read_b64_tr_b16 v[180:181], v237 offset:7680
	ds_read_b64_tr_b16 v[182:183], v237 offset:11776
	ds_read_b64_tr_b16 v[184:185], v237 offset:15872
	ds_read_b64_tr_b16 v[186:187], v237 offset:19968
	ds_read_b64_tr_b16 v[188:189], v237 offset:24064
	ds_read_b64_tr_b16 v[190:191], v237 offset:28160
	ds_read_b64_tr_b16 v[192:193], v237 offset:32256
	s_waitcnt lgkmcnt(8)
	v_mfma_f32_32x32x16_bf16 v[98:113], v[196:199], v[162:165], v[98:113]
	v_mfma_f32_32x32x16_bf16 v[98:113], v[200:203], v[166:169], v[98:113]
	v_mfma_f32_32x32x16_bf16 v[98:113], v[204:207], v[170:173], v[98:113]
	v_mfma_f32_32x32x16_bf16 v[98:113], v[208:211], v[174:177], v[98:113]
	s_waitcnt lgkmcnt(0)
	v_mfma_f32_32x32x16_bf16 v[114:129], v[196:199], v[178:181], v[114:129]
	v_mfma_f32_32x32x16_bf16 v[114:129], v[200:203], v[182:185], v[114:129]
	v_mfma_f32_32x32x16_bf16 v[114:129], v[204:207], v[186:189], v[114:129]
	v_mfma_f32_32x32x16_bf16 v[114:129], v[208:211], v[190:193], v[114:129]
	s_waitcnt vmcnt(0)
	s_barrier
	s_cmp_le_u32 s13, 3
	s_cbranch_scc1 .Lam_nodma_b
	s_add_i32 m0, s39, 0xc000
	s_nop 0
	global_load_lds_dwordx4 v244, s[18:19]
	s_add_i32 m0, s39, 0xc400
	s_nop 0
	global_load_lds_dwordx4 v245, s[18:19]
	s_add_i32 m0, s47, 0xc000
	s_nop 0
	global_load_lds_dwordx4 v246, s[20:21]
	s_add_i32 m0, s47, 0xc400
	s_nop 0
	global_load_lds_dwordx4 v247, s[20:21]
	s_add_i32 m0, s47, 0xc800
	s_nop 0
	global_load_lds_dwordx4 v248, s[20:21]
	s_add_i32 m0, s47, 0xcc00
	s_nop 0
	global_load_lds_dwordx4 v249, s[20:21]
	s_add_u32 s18, s18, 0x40000
	s_addc_u32 s19, s19, 0
	s_add_u32 s20, s20, 0x40000
	s_addc_u32 s21, s21, 0
.Lam_nodma_b:
	s_sub_i32 s13, s13, 2
	s_cmp_gt_u32 s13, 0
	s_cbranch_scc1 .Lam_loop
	v_and_b32_e32 v240, 31, v96
	v_lshl_add_u32 v241, v240, 2, s50
	ds_write_b32 v241, v239 offset:128
	v_lshrrev_b32_e32 v241, 5, v96
	v_lshl_add_u32 v242, v241, 4, s50
	s_waitcnt lgkmcnt(0)
	ds_read_b128 v[212:215], v242 offset:128
	ds_read_b128 v[216:219], v242 offset:160
	ds_read_b128 v[220:223], v242 offset:192
	ds_read_b128 v[224:227], v242 offset:224
	s_lshl_b32 s37, s36, 5
	v_lshl_add_u32 v241, v241, 2, s37
	v_lshlrev_b32_e32 v241, 13, v241
	v_lshl_add_u32 v241, v240, 1, v241
	s_waitcnt lgkmcnt(0)
	v_rcp_f32_e32 v212, v212
	v_rcp_f32_e32 v213, v213
	v_rcp_f32_e32 v214, v214
	v_rcp_f32_e32 v215, v215
	v_rcp_f32_e32 v216, v216
	v_rcp_f32_e32 v217, v217
	v_rcp_f32_e32 v218, v218
	v_rcp_f32_e32 v219, v219
	v_rcp_f32_e32 v220, v220
	v_rcp_f32_e32 v221, v221
	v_rcp_f32_e32 v222, v222
	v_rcp_f32_e32 v223, v223
	v_rcp_f32_e32 v224, v224
	v_rcp_f32_e32 v225, v225
	v_rcp_f32_e32 v226, v226
	v_rcp_f32_e32 v227, v227
	s_nop 0
	v_mov_b32_e32 v240, v241
	v_mul_f32_e32 v162, v0, v212
	v_cvt_pk_bf16_f32 v162, v162, v162
	global_store_short v240, v162, s[22:23]
	v_mul_f32_e32 v163, v16, v212
	v_cvt_pk_bf16_f32 v163, v163, v163
	global_store_short v240, v163, s[22:23] offset:64
	v_mul_f32_e32 v164, v32, v212
	v_cvt_pk_bf16_f32 v164, v164, v164
	global_store_short v240, v164, s[22:23] offset:128
	v_mul_f32_e32 v165, v48, v212
	v_cvt_pk_bf16_f32 v165, v165, v165
	global_store_short v240, v165, s[22:23] offset:192
	v_mul_f32_e32 v166, v64, v212
	v_cvt_pk_bf16_f32 v166, v166, v166
	global_store_short v240, v166, s[22:23] offset:256
	v_mul_f32_e32 v167, v80, v212
	v_cvt_pk_bf16_f32 v167, v167, v167
	global_store_short v240, v167, s[22:23] offset:320
	v_mul_f32_e32 v168, v98, v212
	v_cvt_pk_bf16_f32 v168, v168, v168
	global_store_short v240, v168, s[22:23] offset:384
	v_mul_f32_e32 v169, v114, v212
	v_cvt_pk_bf16_f32 v169, v169, v169
	global_store_short v240, v169, s[22:23] offset:448
	v_add_u32_e32 v240, 0x2000, v241
	v_mul_f32_e32 v170, v1, v213
	v_cvt_pk_bf16_f32 v170, v170, v170
	global_store_short v240, v170, s[22:23]
	v_mul_f32_e32 v171, v17, v213
	v_cvt_pk_bf16_f32 v171, v171, v171
	global_store_short v240, v171, s[22:23] offset:64
	v_mul_f32_e32 v172, v33, v213
	v_cvt_pk_bf16_f32 v172, v172, v172
	global_store_short v240, v172, s[22:23] offset:128
	v_mul_f32_e32 v173, v49, v213
	v_cvt_pk_bf16_f32 v173, v173, v173
	global_store_short v240, v173, s[22:23] offset:192
	v_mul_f32_e32 v174, v65, v213
	v_cvt_pk_bf16_f32 v174, v174, v174
	global_store_short v240, v174, s[22:23] offset:256
	v_mul_f32_e32 v175, v81, v213
	v_cvt_pk_bf16_f32 v175, v175, v175
	global_store_short v240, v175, s[22:23] offset:320
	v_mul_f32_e32 v176, v99, v213
	v_cvt_pk_bf16_f32 v176, v176, v176
	global_store_short v240, v176, s[22:23] offset:384
	v_mul_f32_e32 v177, v115, v213
	v_cvt_pk_bf16_f32 v177, v177, v177
	global_store_short v240, v177, s[22:23] offset:448
	v_add_u32_e32 v240, 0x4000, v241
	v_mul_f32_e32 v178, v2, v214
	v_cvt_pk_bf16_f32 v178, v178, v178
	global_store_short v240, v178, s[22:23]
	v_mul_f32_e32 v179, v18, v214
	v_cvt_pk_bf16_f32 v179, v179, v179
	global_store_short v240, v179, s[22:23] offset:64
	v_mul_f32_e32 v180, v34, v214
	v_cvt_pk_bf16_f32 v180, v180, v180
	global_store_short v240, v180, s[22:23] offset:128
	v_mul_f32_e32 v181, v50, v214
	v_cvt_pk_bf16_f32 v181, v181, v181
	global_store_short v240, v181, s[22:23] offset:192
	v_mul_f32_e32 v182, v66, v214
	v_cvt_pk_bf16_f32 v182, v182, v182
	global_store_short v240, v182, s[22:23] offset:256
	v_mul_f32_e32 v183, v82, v214
	v_cvt_pk_bf16_f32 v183, v183, v183
	global_store_short v240, v183, s[22:23] offset:320
	v_mul_f32_e32 v184, v100, v214
	v_cvt_pk_bf16_f32 v184, v184, v184
	global_store_short v240, v184, s[22:23] offset:384
	v_mul_f32_e32 v185, v116, v214
	v_cvt_pk_bf16_f32 v185, v185, v185
	global_store_short v240, v185, s[22:23] offset:448
	v_add_u32_e32 v240, 0x6000, v241
	v_mul_f32_e32 v186, v3, v215
	v_cvt_pk_bf16_f32 v186, v186, v186
	global_store_short v240, v186, s[22:23]
	v_mul_f32_e32 v187, v19, v215
	v_cvt_pk_bf16_f32 v187, v187, v187
	global_store_short v240, v187, s[22:23] offset:64
	v_mul_f32_e32 v188, v35, v215
	v_cvt_pk_bf16_f32 v188, v188, v188
	global_store_short v240, v188, s[22:23] offset:128
	v_mul_f32_e32 v189, v51, v215
	v_cvt_pk_bf16_f32 v189, v189, v189
	global_store_short v240, v189, s[22:23] offset:192
	v_mul_f32_e32 v190, v67, v215
	v_cvt_pk_bf16_f32 v190, v190, v190
	global_store_short v240, v190, s[22:23] offset:256
	v_mul_f32_e32 v191, v83, v215
	v_cvt_pk_bf16_f32 v191, v191, v191
	global_store_short v240, v191, s[22:23] offset:320
	v_mul_f32_e32 v192, v101, v215
	v_cvt_pk_bf16_f32 v192, v192, v192
	global_store_short v240, v192, s[22:23] offset:384
	v_mul_f32_e32 v193, v117, v215
	v_cvt_pk_bf16_f32 v193, v193, v193
	global_store_short v240, v193, s[22:23] offset:448
	v_add_u32_e32 v240, 0x10000, v241
	v_mul_f32_e32 v162, v4, v216
	v_cvt_pk_bf16_f32 v162, v162, v162
	global_store_short v240, v162, s[22:23]
	v_mul_f32_e32 v163, v20, v216
	v_cvt_pk_bf16_f32 v163, v163, v163
	global_store_short v240, v163, s[22:23] offset:64
	v_mul_f32_e32 v164, v36, v216
	v_cvt_pk_bf16_f32 v164, v164, v164
	global_store_short v240, v164, s[22:23] offset:128
	v_mul_f32_e32 v165, v52, v216
	v_cvt_pk_bf16_f32 v165, v165, v165
	global_store_short v240, v165, s[22:23] offset:192
	v_mul_f32_e32 v166, v68, v216
	v_cvt_pk_bf16_f32 v166, v166, v166
	global_store_short v240, v166, s[22:23] offset:256
	v_mul_f32_e32 v167, v84, v216
	v_cvt_pk_bf16_f32 v167, v167, v167
	global_store_short v240, v167, s[22:23] offset:320
	v_mul_f32_e32 v168, v102, v216
	v_cvt_pk_bf16_f32 v168, v168, v168
	global_store_short v240, v168, s[22:23] offset:384
	v_mul_f32_e32 v169, v118, v216
	v_cvt_pk_bf16_f32 v169, v169, v169
	global_store_short v240, v169, s[22:23] offset:448
	v_add_u32_e32 v240, 0x12000, v241
	v_mul_f32_e32 v170, v5, v217
	v_cvt_pk_bf16_f32 v170, v170, v170
	global_store_short v240, v170, s[22:23]
	v_mul_f32_e32 v171, v21, v217
	v_cvt_pk_bf16_f32 v171, v171, v171
	global_store_short v240, v171, s[22:23] offset:64
	v_mul_f32_e32 v172, v37, v217
	v_cvt_pk_bf16_f32 v172, v172, v172
	global_store_short v240, v172, s[22:23] offset:128
	v_mul_f32_e32 v173, v53, v217
	v_cvt_pk_bf16_f32 v173, v173, v173
	global_store_short v240, v173, s[22:23] offset:192
	v_mul_f32_e32 v174, v69, v217
	v_cvt_pk_bf16_f32 v174, v174, v174
	global_store_short v240, v174, s[22:23] offset:256
	v_mul_f32_e32 v175, v85, v217
	v_cvt_pk_bf16_f32 v175, v175, v175
	global_store_short v240, v175, s[22:23] offset:320
	v_mul_f32_e32 v176, v103, v217
	v_cvt_pk_bf16_f32 v176, v176, v176
	global_store_short v240, v176, s[22:23] offset:384
	v_mul_f32_e32 v177, v119, v217
	v_cvt_pk_bf16_f32 v177, v177, v177
	global_store_short v240, v177, s[22:23] offset:448
	v_add_u32_e32 v240, 0x14000, v241
	v_mul_f32_e32 v178, v6, v218
	v_cvt_pk_bf16_f32 v178, v178, v178
	global_store_short v240, v178, s[22:23]
	v_mul_f32_e32 v179, v22, v218
	v_cvt_pk_bf16_f32 v179, v179, v179
	global_store_short v240, v179, s[22:23] offset:64
	v_mul_f32_e32 v180, v38, v218
	v_cvt_pk_bf16_f32 v180, v180, v180
	global_store_short v240, v180, s[22:23] offset:128
	v_mul_f32_e32 v181, v54, v218
	v_cvt_pk_bf16_f32 v181, v181, v181
	global_store_short v240, v181, s[22:23] offset:192
	v_mul_f32_e32 v182, v70, v218
	v_cvt_pk_bf16_f32 v182, v182, v182
	global_store_short v240, v182, s[22:23] offset:256
	v_mul_f32_e32 v183, v86, v218
	v_cvt_pk_bf16_f32 v183, v183, v183
	global_store_short v240, v183, s[22:23] offset:320
	v_mul_f32_e32 v184, v104, v218
	v_cvt_pk_bf16_f32 v184, v184, v184
	global_store_short v240, v184, s[22:23] offset:384
	v_mul_f32_e32 v185, v120, v218
	v_cvt_pk_bf16_f32 v185, v185, v185
	global_store_short v240, v185, s[22:23] offset:448
	v_add_u32_e32 v240, 0x16000, v241
	v_mul_f32_e32 v186, v7, v219
	v_cvt_pk_bf16_f32 v186, v186, v186
	global_store_short v240, v186, s[22:23]
	v_mul_f32_e32 v187, v23, v219
	v_cvt_pk_bf16_f32 v187, v187, v187
	global_store_short v240, v187, s[22:23] offset:64
	v_mul_f32_e32 v188, v39, v219
	v_cvt_pk_bf16_f32 v188, v188, v188
	global_store_short v240, v188, s[22:23] offset:128
	v_mul_f32_e32 v189, v55, v219
	v_cvt_pk_bf16_f32 v189, v189, v189
	global_store_short v240, v189, s[22:23] offset:192
	v_mul_f32_e32 v190, v71, v219
	v_cvt_pk_bf16_f32 v190, v190, v190
	global_store_short v240, v190, s[22:23] offset:256
	v_mul_f32_e32 v191, v87, v219
	v_cvt_pk_bf16_f32 v191, v191, v191
	global_store_short v240, v191, s[22:23] offset:320
	v_mul_f32_e32 v192, v105, v219
	v_cvt_pk_bf16_f32 v192, v192, v192
	global_store_short v240, v192, s[22:23] offset:384
	v_mul_f32_e32 v193, v121, v219
	v_cvt_pk_bf16_f32 v193, v193, v193
	global_store_short v240, v193, s[22:23] offset:448
	v_add_u32_e32 v240, 0x20000, v241
	v_mul_f32_e32 v162, v8, v220
	v_cvt_pk_bf16_f32 v162, v162, v162
	global_store_short v240, v162, s[22:23]
	v_mul_f32_e32 v163, v24, v220
	v_cvt_pk_bf16_f32 v163, v163, v163
	global_store_short v240, v163, s[22:23] offset:64
	v_mul_f32_e32 v164, v40, v220
	v_cvt_pk_bf16_f32 v164, v164, v164
	global_store_short v240, v164, s[22:23] offset:128
	v_mul_f32_e32 v165, v56, v220
	v_cvt_pk_bf16_f32 v165, v165, v165
	global_store_short v240, v165, s[22:23] offset:192
	v_mul_f32_e32 v166, v72, v220
	v_cvt_pk_bf16_f32 v166, v166, v166
	global_store_short v240, v166, s[22:23] offset:256
	v_mul_f32_e32 v167, v88, v220
	v_cvt_pk_bf16_f32 v167, v167, v167
	global_store_short v240, v167, s[22:23] offset:320
	v_mul_f32_e32 v168, v106, v220
	v_cvt_pk_bf16_f32 v168, v168, v168
	global_store_short v240, v168, s[22:23] offset:384
	v_mul_f32_e32 v169, v122, v220
	v_cvt_pk_bf16_f32 v169, v169, v169
	global_store_short v240, v169, s[22:23] offset:448
	v_add_u32_e32 v240, 0x22000, v241
	v_mul_f32_e32 v170, v9, v221
	v_cvt_pk_bf16_f32 v170, v170, v170
	global_store_short v240, v170, s[22:23]
	v_mul_f32_e32 v171, v25, v221
	v_cvt_pk_bf16_f32 v171, v171, v171
	global_store_short v240, v171, s[22:23] offset:64
	v_mul_f32_e32 v172, v41, v221
	v_cvt_pk_bf16_f32 v172, v172, v172
	global_store_short v240, v172, s[22:23] offset:128
	v_mul_f32_e32 v173, v57, v221
	v_cvt_pk_bf16_f32 v173, v173, v173
	global_store_short v240, v173, s[22:23] offset:192
	v_mul_f32_e32 v174, v73, v221
	v_cvt_pk_bf16_f32 v174, v174, v174
	global_store_short v240, v174, s[22:23] offset:256
	v_mul_f32_e32 v175, v89, v221
	v_cvt_pk_bf16_f32 v175, v175, v175
	global_store_short v240, v175, s[22:23] offset:320
	v_mul_f32_e32 v176, v107, v221
	v_cvt_pk_bf16_f32 v176, v176, v176
	global_store_short v240, v176, s[22:23] offset:384
	v_mul_f32_e32 v177, v123, v221
	v_cvt_pk_bf16_f32 v177, v177, v177
	global_store_short v240, v177, s[22:23] offset:448
	v_add_u32_e32 v240, 0x24000, v241
	v_mul_f32_e32 v178, v10, v222
	v_cvt_pk_bf16_f32 v178, v178, v178
	global_store_short v240, v178, s[22:23]
	v_mul_f32_e32 v179, v26, v222
	v_cvt_pk_bf16_f32 v179, v179, v179
	global_store_short v240, v179, s[22:23] offset:64
	v_mul_f32_e32 v180, v42, v222
	v_cvt_pk_bf16_f32 v180, v180, v180
	global_store_short v240, v180, s[22:23] offset:128
	v_mul_f32_e32 v181, v58, v222
	v_cvt_pk_bf16_f32 v181, v181, v181
	global_store_short v240, v181, s[22:23] offset:192
	v_mul_f32_e32 v182, v74, v222
	v_cvt_pk_bf16_f32 v182, v182, v182
	global_store_short v240, v182, s[22:23] offset:256
	v_mul_f32_e32 v183, v90, v222
	v_cvt_pk_bf16_f32 v183, v183, v183
	global_store_short v240, v183, s[22:23] offset:320
	v_mul_f32_e32 v184, v108, v222
	v_cvt_pk_bf16_f32 v184, v184, v184
	global_store_short v240, v184, s[22:23] offset:384
	v_mul_f32_e32 v185, v124, v222
	v_cvt_pk_bf16_f32 v185, v185, v185
	global_store_short v240, v185, s[22:23] offset:448
	v_add_u32_e32 v240, 0x26000, v241
	v_mul_f32_e32 v186, v11, v223
	v_cvt_pk_bf16_f32 v186, v186, v186
	global_store_short v240, v186, s[22:23]
	v_mul_f32_e32 v187, v27, v223
	v_cvt_pk_bf16_f32 v187, v187, v187
	global_store_short v240, v187, s[22:23] offset:64
	v_mul_f32_e32 v188, v43, v223
	v_cvt_pk_bf16_f32 v188, v188, v188
	global_store_short v240, v188, s[22:23] offset:128
	v_mul_f32_e32 v189, v59, v223
	v_cvt_pk_bf16_f32 v189, v189, v189
	global_store_short v240, v189, s[22:23] offset:192
	v_mul_f32_e32 v190, v75, v223
	v_cvt_pk_bf16_f32 v190, v190, v190
	global_store_short v240, v190, s[22:23] offset:256
	v_mul_f32_e32 v191, v91, v223
	v_cvt_pk_bf16_f32 v191, v191, v191
	global_store_short v240, v191, s[22:23] offset:320
	v_mul_f32_e32 v192, v109, v223
	v_cvt_pk_bf16_f32 v192, v192, v192
	global_store_short v240, v192, s[22:23] offset:384
	v_mul_f32_e32 v193, v125, v223
	v_cvt_pk_bf16_f32 v193, v193, v193
	global_store_short v240, v193, s[22:23] offset:448
	v_add_u32_e32 v240, 0x30000, v241
	v_mul_f32_e32 v162, v12, v224
	v_cvt_pk_bf16_f32 v162, v162, v162
	global_store_short v240, v162, s[22:23]
	v_mul_f32_e32 v163, v28, v224
	v_cvt_pk_bf16_f32 v163, v163, v163
	global_store_short v240, v163, s[22:23] offset:64
	v_mul_f32_e32 v164, v44, v224
	v_cvt_pk_bf16_f32 v164, v164, v164
	global_store_short v240, v164, s[22:23] offset:128
	v_mul_f32_e32 v165, v60, v224
	v_cvt_pk_bf16_f32 v165, v165, v165
	global_store_short v240, v165, s[22:23] offset:192
	v_mul_f32_e32 v166, v76, v224
	v_cvt_pk_bf16_f32 v166, v166, v166
	global_store_short v240, v166, s[22:23] offset:256
	v_mul_f32_e32 v167, v92, v224
	v_cvt_pk_bf16_f32 v167, v167, v167
	global_store_short v240, v167, s[22:23] offset:320
	v_mul_f32_e32 v168, v110, v224
	v_cvt_pk_bf16_f32 v168, v168, v168
	global_store_short v240, v168, s[22:23] offset:384
	v_mul_f32_e32 v169, v126, v224
	v_cvt_pk_bf16_f32 v169, v169, v169
	global_store_short v240, v169, s[22:23] offset:448
	v_add_u32_e32 v240, 0x32000, v241
	v_mul_f32_e32 v170, v13, v225
	v_cvt_pk_bf16_f32 v170, v170, v170
	global_store_short v240, v170, s[22:23]
	v_mul_f32_e32 v171, v29, v225
	v_cvt_pk_bf16_f32 v171, v171, v171
	global_store_short v240, v171, s[22:23] offset:64
	v_mul_f32_e32 v172, v45, v225
	v_cvt_pk_bf16_f32 v172, v172, v172
	global_store_short v240, v172, s[22:23] offset:128
	v_mul_f32_e32 v173, v61, v225
	v_cvt_pk_bf16_f32 v173, v173, v173
	global_store_short v240, v173, s[22:23] offset:192
	v_mul_f32_e32 v174, v77, v225
	v_cvt_pk_bf16_f32 v174, v174, v174
	global_store_short v240, v174, s[22:23] offset:256
	v_mul_f32_e32 v175, v93, v225
	v_cvt_pk_bf16_f32 v175, v175, v175
	global_store_short v240, v175, s[22:23] offset:320
	v_mul_f32_e32 v176, v111, v225
	v_cvt_pk_bf16_f32 v176, v176, v176
	global_store_short v240, v176, s[22:23] offset:384
	v_mul_f32_e32 v177, v127, v225
	v_cvt_pk_bf16_f32 v177, v177, v177
	global_store_short v240, v177, s[22:23] offset:448
	v_add_u32_e32 v240, 0x34000, v241
	v_mul_f32_e32 v178, v14, v226
	v_cvt_pk_bf16_f32 v178, v178, v178
	global_store_short v240, v178, s[22:23]
	v_mul_f32_e32 v179, v30, v226
	v_cvt_pk_bf16_f32 v179, v179, v179
	global_store_short v240, v179, s[22:23] offset:64
	v_mul_f32_e32 v180, v46, v226
	v_cvt_pk_bf16_f32 v180, v180, v180
	global_store_short v240, v180, s[22:23] offset:128
	v_mul_f32_e32 v181, v62, v226
	v_cvt_pk_bf16_f32 v181, v181, v181
	global_store_short v240, v181, s[22:23] offset:192
	v_mul_f32_e32 v182, v78, v226
	v_cvt_pk_bf16_f32 v182, v182, v182
	global_store_short v240, v182, s[22:23] offset:256
	v_mul_f32_e32 v183, v94, v226
	v_cvt_pk_bf16_f32 v183, v183, v183
	global_store_short v240, v183, s[22:23] offset:320
	v_mul_f32_e32 v184, v112, v226
	v_cvt_pk_bf16_f32 v184, v184, v184
	global_store_short v240, v184, s[22:23] offset:384
	v_mul_f32_e32 v185, v128, v226
	v_cvt_pk_bf16_f32 v185, v185, v185
	global_store_short v240, v185, s[22:23] offset:448
	v_add_u32_e32 v240, 0x36000, v241
	v_mul_f32_e32 v186, v15, v227
	v_cvt_pk_bf16_f32 v186, v186, v186
	global_store_short v240, v186, s[22:23]
	v_mul_f32_e32 v187, v31, v227
	v_cvt_pk_bf16_f32 v187, v187, v187
	global_store_short v240, v187, s[22:23] offset:64
	v_mul_f32_e32 v188, v47, v227
	v_cvt_pk_bf16_f32 v188, v188, v188
	global_store_short v240, v188, s[22:23] offset:128
	v_mul_f32_e32 v189, v63, v227
	v_cvt_pk_bf16_f32 v189, v189, v189
	global_store_short v240, v189, s[22:23] offset:192
	v_mul_f32_e32 v190, v79, v227
	v_cvt_pk_bf16_f32 v190, v190, v190
	global_store_short v240, v190, s[22:23] offset:256
	v_mul_f32_e32 v191, v95, v227
	v_cvt_pk_bf16_f32 v191, v191, v191
	global_store_short v240, v191, s[22:23] offset:320
	v_mul_f32_e32 v192, v113, v227
	v_cvt_pk_bf16_f32 v192, v192, v192
	global_store_short v240, v192, s[22:23] offset:384
	v_mul_f32_e32 v193, v129, v227
	v_cvt_pk_bf16_f32 v193, v193, v193
	global_store_short v240, v193, s[22:23] offset:448
	s_waitcnt lgkmcnt(0)
	s_barrier
.Lam_skip:
	s_brev_b32 s30, 64
	v_readlane_b32 s31, v254, 63
	s_movk_i32 s61, 0x1000
	s_mov_b64 s[6:7], 0
